# norm phase (layers 1-3): waves with a ctx row and its split-K fold take no latent row pair, the others four (was 1 / 3)
# speedup vs baseline: 1.0057x; 1.0031x over previous
.LBB0_98:
	s_cmp_eq_u32 s22, 0
	v_readlane_b32 s8, v254, 38
	s_cselect_b64 s[6:7], -1, 0
	v_readlane_b32 s9, v254, 39
	s_or_b64 s[6:7], s[8:9], s[6:7]
	v_readlane_b32 s24, v253, 16
	v_mov_b32_e32 v158, 0x1000
	s_and_b64 vcc, exec, s[6:7]
	v_readlane_b32 s25, v253, 17
	s_cbranch_vccnz .LBB0_104
	s_and_saveexec_b64 s[6:7], s[36:37]
	s_xor_b64 s[6:7], exec, s[6:7]
	v_lshlrev_b32_e32 v32, 2, v177
	v_add_u32_e32 v177, 0xfffff000, v32
	v_add_u32_e32 v158, 0xfffff004, v32
	s_andn2_saveexec_b64 s[6:7], s[6:7]
	v_mov_b32_e32 v158, v177
	s_or_b64 exec, exec, s[6:7]
	s_mov_b32 s6, 1
	v_cmp_lt_i32_e32 vcc, v177, v158
	s_and_saveexec_b64 s[26:27], vcc
	s_cbranch_execnz .LBB0_105
	s_branch .LBB0_107
